# attention: causal-masked diagonal tiles also take the overlapped fast path (mask applied in place with pipelined v_cmp/v_cndmask); old serialized masked body removed
# baseline (speedup 1.0000x reference)
; #define LAS __attribute__((address_space(3)))
; DI void rope_cs(int pos, int j, float& c, float& s) {
;     const int jl = j & 3, jh = j >> 2;
;     const double fb = jl == 0 ? 1.0 : jl == 1 ? 0.5623413251903491 : jl == 2 ? 0.31622776601683794 : 0.1778279410038923;
;     const double fs = jh == 0 ? 1.0 : jh == 1 ? 0.1 : jh == 2 ? 0.01 : 0.001;
; DI void attn_unit(int b, int h, int qb, const bf16* Qb, const bf16* Kb, const bf16* Vt, const int* positions, bf16* O, LAS unsigned char* lds, int tid) {
;     const int wave = __builtin_amdgcn_readfirstlane(tid >> 6), lane = tid & 63, r32 = lane & 31, hi = lane >> 5;
;     const int rowbase = b * T, q0 = qb * 256, qrow = q0 + 32 * wave + r32;
;     const int kkey0 = tid / 12, kc0 = tid % 12, vd = tid >> 3, vc = tid & 7;
;     const bf16* kg0 = Kb + (size_t)(rowbase + kkey0) * 768 + h * 96 + kc0 * 8;
;     const bf16* vg = Vt + (size_t)(h * 64 + vd) * VT_LD + rowbase + vc * 8;
;     const int NT = (q0 + 256) / 64, NTF = q0 / 64;
;     const int kp1 = tid < 256 ? 512 + tid : tid;
;     const int kkey1 = kp1 / 12, kc1 = kp1 % 12;
;     const bf16* kg1 = Kb + (size_t)(rowbase + kkey1) * 768 + h * 96 + kc1 * 8;
;     u32x4 kA0, kA1, vA, kB0, kB1, vB, kC0, kC1, vC;
;     ...
;     AT_ISSUE(A, 0); AT_ISSUE(B, 1); AT_ISSUE(C, 2);
;     bf16x8 qr[6];
;     {
;         const bf16* qp = Qb + (size_t)(rowbase + qrow) * 768 + h * 96 + 8 * hi;
;         float qv[6][8];
; #pragma unroll
;         for (int d0 = 0; d0 < 6; ++d0) { const u32x4 a = *(const u32x4*)(qp + 16 * d0);
;             qv[d0][0] = bflo(a.x); qv[d0][1] = bfhi(a.x); qv[d0][2] = bflo(a.y); qv[d0][3] = bfhi(a.y); qv[d0][4] = bflo(a.z); qv[d0][5] = bfhi(a.z); qv[d0][6] = bflo(a.w); qv[d0][7] = bfhi(a.w); }
;         const int pos = positions[rowbase + qrow];
; #pragma unroll
;         for (int i = 0; i < 8; ++i) { float c, s; rope_cs(pos, 8 * hi + i, c, s); const float x1 = qv[4][i], x2 = qv[5][i]; qv[4][i] = x1 * c - x2 * s; qv[5][i] = x1 * s + x2 * c; }
;         const float C2 = 0.10206207261596575f * 1.4426950408889634f;
; #pragma unroll
;         for (int d0 = 0; d0 < 6; ++d0) { u32x4 p; p.x = pk2(qv[d0][0] * C2, qv[d0][1] * C2); p.y = pk2(qv[d0][2] * C2, qv[d0][3] * C2); p.z = pk2(qv[d0][4] * C2, qv[d0][5] * C2); p.w = pk2(qv[d0][6] * C2, qv[d0][7] * C2);
;             qr[d0] = __builtin_bit_cast(bf16x8, p); }
;     }
;     AT_COMMIT(A, 0);
;     AT_ISSUE(A, 3);
.LBB0_845:
	s_or_b64 exec, exec, s[18:19]
	s_and_b32 s18, s12, 7
	s_or_b32 s20, s18, s25
	s_and_b32 s21, s12, 63
	s_and_b64 s[18:19], s[8:9], exec
	s_cselect_b32 s18, s20, s21
	s_ashr_i32 s12, s12, s26
	s_sub_i32 s22, 15, s12
	s_lshl_b32 s12, s18, 9
	s_and_b32 s34, s12, 0xfffff000
	v_or_b32_e32 v0, s34, v202
	s_and_b32 s20, s18, 7
	v_mad_i64_i32 v[2:3], s[18:19], v0, s27, v[186:187]
	s_lshl_b32 s18, s20, 6
	s_mul_i32 s12, s20, 0x60
	v_add_u32_e32 v0, s18, v198
	s_lshl_b32 s12, s12, 1
	v_mul_u32_u24_e32 v0, 0x8040, v0
	v_lshl_add_u64 v[2:3], v[2:3], 0, s[12:13]
	v_lshlrev_b32_e32 v0, 1, v0
	s_lshl_b32 s23, s22, 8
	v_lshl_add_u64 v[190:191], v[2:3], 0, v[182:183]
	v_lshl_add_u64 v[2:3], s[6:7], 0, v[0:1]
	s_ashr_i32 s35, s34, 31
	v_lshl_add_u64 v[2:3], s[34:35], 1, v[2:3]
	v_mov_b32_e32 v159, v1
	s_add_i32 s19, s23, 0x100
	v_or_b32_e32 v0, s34, v203
	v_lshl_add_u64 v[192:193], v[2:3], 0, v[158:159]
	s_ashr_i32 s19, s19, 6
	v_mad_i64_i32 v[2:3], s[20:21], v0, s27, v[186:187]
	v_lshl_add_u64 v[2:3], v[2:3], 0, s[12:13]
	v_mov_b32_e32 v185, v1
	s_add_i32 s20, s19, -1
	v_lshl_add_u64 v[194:195], v[2:3], 0, v[184:185]
	s_min_i32 s21, s20, 0
	v_mad_i64_i32 v[2:3], s[36:37], s21, v161, v[190:191]
	v_mad_i64_i32 v[6:7], s[36:37], s21, v161, v[194:195]
	s_lshl_b32 s36, s21, 6
	s_ashr_i32 s37, s36, 31
	v_lshl_add_u64 v[10:11], s[36:37], 1, v[192:193]
	global_load_dwordx4 v[2:5], v[2:3], off
	s_nop 0
	global_load_dwordx4 v[6:9], v[6:7], off
	s_nop 0
	global_load_dwordx4 v[10:13], v[10:11], off
	v_readfirstlane_b32 s21, v197
	s_lshr_b32 s21, s21, 1
	s_and_b32 s21, s21, 0x7fffffe0
	s_add_i32 s23, s21, s23
	v_or_b32_e32 v49, s23, v201
	v_add_u32_e32 v188, s34, v49
	v_ashrrev_i32_e32 v189, 31, v188
	s_cmp_lt_i32 s19, 1
	s_mov_b32 s21, 0
	s_waitcnt vmcnt(2)
	ds_write_b128 v209, v[2:5]
	s_waitcnt vmcnt(1)
	ds_write_b128 v210, v[6:9]
	s_waitcnt vmcnt(0)
	ds_write2_b64 v211, v[10:11], v[12:13] offset1:1
	s_cbranch_scc1 .LBB0_868
	v_readlane_b32 s36, v253, 3
	v_readlane_b32 s38, v253, 5
	v_readlane_b32 s39, v253, 6
	s_min_i32 s33, s20, 1
	v_readlane_b32 s37, v253, 4
	v_lshl_add_u64 v[2:3], v[188:189], 2, s[38:39]
	global_load_dword v0, v[2:3], off
	v_lshl_add_u64 v[2:3], v[162:163], 0, s[12:13]
	v_mad_i64_i32 v[2:3], s[34:35], v188, s27, v[2:3]
	global_load_dwordx4 v[14:17], v[2:3], off offset:96
	global_load_dwordx4 v[18:21], v[2:3], off offset:128
	global_load_dwordx4 v[22:25], v[2:3], off offset:160
	s_min_i32 s38, s20, 2
	v_mad_i64_i32 v[26:27], s[34:35], s33, v161, v[190:191]
	v_mad_i64_i32 v[4:5], s[34:35], s33, v161, v[194:195]
	s_lshl_b32 s34, s33, 6
	v_mad_i64_i32 v[6:7], s[36:37], s38, v161, v[190:191]
	v_mad_i64_i32 v[8:9], s[36:37], s38, v161, v[194:195]
	s_lshl_b32 s36, s38, 6
	s_ashr_i32 s35, s34, 31
	s_ashr_i32 s37, s36, 31
	v_lshl_add_u64 v[28:29], s[34:35], 1, v[192:193]
	global_load_dwordx4 v[98:101], v[6:7], off
	global_load_dwordx4 v[102:105], v[8:9], off
	s_nop 0
	global_load_dwordx4 v[6:9], v[2:3], off offset:32
	global_load_dwordx4 v[10:13], v[2:3], off offset:64
	v_lshl_add_u64 v[30:31], s[36:37], 1, v[192:193]
	global_load_dwordx4 v[106:109], v[4:5], off
	global_load_dwordx4 v[110:113], v[28:29], off
	global_load_dwordx4 v[114:117], v[30:31], off
	s_nop 0
	global_load_dwordx4 v[2:5], v[2:3], off
	s_nop 0
	global_load_dwordx4 v[130:133], v[26:27], off
	global_load_dwordx4 v[134:137], v[192:193], off offset:384
	s_lshl_b32 s12, s22, 2
	s_or_b32 s22, s23, 31
	v_mov_b32_e32 v48, 0
	s_mov_b32 s23, 0
	v_readlane_b32 s40, v253, 7
	v_readlane_b32 s41, v253, 8
	v_readlane_b32 s42, v253, 9
	v_readlane_b32 s43, v253, 10
	v_readlane_b32 s44, v253, 11
	v_readlane_b32 s45, v253, 12
	v_readlane_b32 s46, v253, 13
	v_readlane_b32 s47, v253, 14
	v_readlane_b32 s48, v253, 15
	v_readlane_b32 s49, v253, 16
	v_readlane_b32 s50, v253, 17
	v_readlane_b32 s51, v253, 18
	s_waitcnt vmcnt(13)
	v_cvt_f64_i32_e32 v[28:29], v0
	v_mul_f64 v[30:31], v[164:165], v[28:29]
	v_mul_f64 v[32:33], v[166:167], v[28:29]
	v_mul_f64 v[44:45], v[30:31], s[14:15]
	v_mul_f64 v[46:47], v[32:33], s[14:15]
	v_rndne_f64_e32 v[44:45], v[44:45]
	v_rndne_f64_e32 v[46:47], v[46:47]
	v_fma_f64 v[30:31], v[30:31], s[14:15], -v[44:45]
	v_fma_f64 v[32:33], v[32:33], s[14:15], -v[46:47]
	v_mul_f64 v[34:35], v[168:169], v[28:29]
	v_mul_f64 v[36:37], v[170:171], v[28:29]
	v_cvt_f32_f64_e32 v0, v[30:31]
	v_cvt_f32_f64_e32 v33, v[32:33]
	v_mul_f64 v[38:39], v[172:173], v[28:29]
	v_mul_f64 v[40:41], v[174:175], v[28:29]
	v_mul_f64 v[42:43], v[176:177], v[28:29]
	v_mul_f64 v[28:29], v[178:179], v[28:29]
	v_mul_f64 v[50:51], v[34:35], s[14:15]
	v_mul_f64 v[52:53], v[36:37], s[14:15]
	v_cos_f32_e32 v32, v0
	v_sin_f32_e32 v31, v33
	v_cos_f32_e32 v33, v33
	v_mul_f64 v[60:61], v[28:29], s[14:15]
	v_rndne_f64_e32 v[50:51], v[50:51]
	v_rndne_f64_e32 v[52:53], v[52:53]
	v_sin_f32_e32 v30, v0
	v_rndne_f64_e32 v[60:61], v[60:61]
	v_fma_f64 v[34:35], v[34:35], s[14:15], -v[50:51]
	v_fma_f64 v[36:37], v[36:37], s[14:15], -v[52:53]
	v_mul_f64 v[54:55], v[38:39], s[14:15]
	v_mul_f64 v[56:57], v[40:41], s[14:15]
	v_fma_f64 v[28:29], v[28:29], s[14:15], -v[60:61]
	v_cvt_f32_f64_e32 v35, v[34:35]
	v_cvt_f32_f64_e32 v37, v[36:37]
	s_waitcnt vmcnt(10)
; DI unsigned pk2(float lo, float hi) { f32x2_t v = {lo, hi}; bf16x2_t b = __builtin_convertvector(v, bf16x2_t); return __builtin_bit_cast(unsigned, b); }
; DI float bflo(unsigned u) { return __uint_as_float(u << 16); }
; DI float bfhi(unsigned u) { return __uint_as_float(u & 0xffff0000u); }
; #define AT_ISSUE(S, t) do { const int tt_ = (t) < NT ? (t) : NT - 1; const size_t ko_ = (size_t)tt_ * 64 * 768; \
;         k##S##0 = *(const u32x4*)(kg0 + ko_); k##S##1 = *(const u32x4*)(kg1 + ko_); v##S = *(const u32x4*)(vg + tt_ * 64); } while (0)
; #define AT_TILE(t, stage) do { if ((t) < NT && 64 * (t) <= qmax_w) { const LAS unsigned char* Ks_ = lds + (stage) * AT_STAGE; \
;         attn_tile((t) >= NTF, Ks_, Ks_ + AT_KS, qr, negm, mrun, lrun, o0, o1, 64 * (t), qrow, r32, hi); AT_DUP(t) } } while (0)
; DI void attn_unit(int b, int h, int qb, const bf16* Qb, const bf16* Kb, const bf16* Vt, const int* positions, bf16* O, LAS unsigned char* lds, int tid) {
;     ...
;         for (int d0 = 0; d0 < 6; ++d0) { const u32x4 a = *(const u32x4*)(qp + 16 * d0);
;             qv[d0][0] = bflo(a.x); qv[d0][1] = bfhi(a.x); qv[d0][2] = bflo(a.y); qv[d0][3] = bfhi(a.y); qv[d0][4] = bflo(a.z); qv[d0][5] = bfhi(a.z); qv[d0][6] = bflo(a.w); qv[d0][7] = bfhi(a.w); }
;         const int pos = positions[rowbase + qrow];
; #pragma unroll
;         for (int i = 0; i < 8; ++i) { float c, s; rope_cs(pos, 8 * hi + i, c, s); const float x1 = qv[4][i], x2 = qv[5][i]; qv[4][i] = x1 * c - x2 * s; qv[5][i] = x1 * s + x2 * c; }
;         const float C2 = 0.10206207261596575f * 1.4426950408889634f;
; #pragma unroll
;         for (int d0 = 0; d0 < 6; ++d0) { u32x4 p; p.x = pk2(qv[d0][0] * C2, qv[d0][1] * C2); p.y = pk2(qv[d0][2] * C2, qv[d0][3] * C2); p.z = pk2(qv[d0][4] * C2, qv[d0][5] * C2); p.w = pk2(qv[d0][6] * C2, qv[d0][7] * C2);
;             qr[d0] = __builtin_bit_cast(bf16x8, p); }
;     }
;     AT_COMMIT(A, 0);
;     AT_ISSUE(A, 3);
;     float mrun = 0.f, lrun = 0.f;
;     f32x16 o0 = {}, o1 = {}, negm = {};
;     ...
;     for (int t = 0; t < NT; t += 3) {
;         __syncthreads();
;         AT_COMMIT(B, 1); AT_ISSUE(B, t + 4);
;         AT_TILE(t, 0);
;         __syncthreads();
;         AT_COMMIT(C, 2); AT_ISSUE(C, t + 5);
;         AT_TILE(t + 1, 1);
;         __syncthreads();
;         AT_COMMIT(A, 0); AT_ISSUE(A, t + 6);
;         AT_TILE(t + 2, 2);
;     }
	v_lshlrev_b32_e32 v46, 16, v22
	v_and_b32_e32 v47, 0xffff0000, v22
	v_rndne_f64_e32 v[54:55], v[54:55]
	v_rndne_f64_e32 v[56:57], v[56:57]
	v_sin_f32_e32 v34, v35
	v_cos_f32_e32 v36, v35
	v_sin_f32_e32 v35, v37
	v_cos_f32_e32 v37, v37
	v_cvt_f32_f64_e32 v0, v[28:29]
	v_lshlrev_b32_e32 v28, 16, v18
	v_and_b32_e32 v29, 0xffff0000, v18
	v_pk_mul_f32 v[50:51], v[32:33], v[46:47]
	v_fma_f64 v[38:39], v[38:39], s[14:15], -v[54:55]
	v_fma_f64 v[40:41], v[40:41], s[14:15], -v[56:57]
	v_pk_fma_f32 v[50:51], v[30:31], v[28:29], v[50:51]
	v_pk_mul_f32 v[30:31], v[30:31], v[46:47]
	v_cvt_f32_f64_e32 v39, v[38:39]
	v_cvt_f32_f64_e32 v41, v[40:41]
	v_pk_fma_f32 v[28:29], v[32:33], v[28:29], v[30:31] neg_lo:[0,0,1] neg_hi:[0,0,1]
	v_mul_f64 v[58:59], v[42:43], s[14:15]
	v_sin_f32_e32 v38, v39
	v_cos_f32_e32 v40, v39
	v_sin_f32_e32 v39, v41
	v_cos_f32_e32 v41, v41
	v_pk_mul_f32 v[28:29], v[28:29], s[16:17] op_sel_hi:[1,0]
	v_lshlrev_b32_e32 v22, 16, v23
	v_and_b32_e32 v23, 0xffff0000, v23
	v_rndne_f64_e32 v[58:59], v[58:59]
	v_cvt_pk_bf16_f32 v122, v28, v29
	v_lshlrev_b32_e32 v18, 16, v19
	v_and_b32_e32 v19, 0xffff0000, v19
	v_pk_mul_f32 v[28:29], v[36:37], v[22:23]
	v_pk_mul_f32 v[22:23], v[34:35], v[22:23]
	v_fma_f64 v[42:43], v[42:43], s[14:15], -v[58:59]
	v_pk_fma_f32 v[28:29], v[34:35], v[18:19], v[28:29]
	v_pk_fma_f32 v[18:19], v[36:37], v[18:19], v[22:23] neg_lo:[0,0,1] neg_hi:[0,0,1]
	v_cvt_f32_f64_e32 v43, v[42:43]
	v_pk_mul_f32 v[28:29], v[28:29], s[16:17] op_sel_hi:[1,0]
	v_pk_mul_f32 v[18:19], v[18:19], s[16:17] op_sel_hi:[1,0]
	v_lshlrev_b32_e32 v22, 16, v24
	v_and_b32_e32 v23, 0xffff0000, v24
	v_sin_f32_e32 v42, v43
	v_cos_f32_e32 v44, v43
	v_sin_f32_e32 v43, v0
	v_cos_f32_e32 v45, v0
	v_cvt_pk_bf16_f32 v119, v28, v29
	v_cvt_pk_bf16_f32 v123, v18, v19
	v_lshlrev_b32_e32 v18, 16, v20
	v_and_b32_e32 v19, 0xffff0000, v20
	v_pk_mul_f32 v[28:29], v[40:41], v[22:23]
	v_pk_mul_f32 v[22:23], v[38:39], v[22:23]
	v_pk_fma_f32 v[28:29], v[38:39], v[18:19], v[28:29]
	v_pk_fma_f32 v[18:19], v[40:41], v[18:19], v[22:23] neg_lo:[0,0,1] neg_hi:[0,0,1]
	v_lshlrev_b32_e32 v20, 16, v25
	v_pk_mul_f32 v[18:19], v[18:19], s[16:17] op_sel_hi:[1,0]
	v_pk_mul_f32 v[50:51], v[50:51], s[16:17] op_sel_hi:[1,0]
	v_cvt_pk_bf16_f32 v124, v18, v19
	v_lshlrev_b32_e32 v18, 16, v21
	v_and_b32_e32 v19, 0xffff0000, v21
	v_and_b32_e32 v21, 0xffff0000, v25
	v_pk_mul_f32 v[22:23], v[44:45], v[20:21]
	v_pk_mul_f32 v[20:21], v[42:43], v[20:21]
	v_pk_fma_f32 v[22:23], v[42:43], v[18:19], v[22:23]
	v_pk_fma_f32 v[18:19], v[44:45], v[18:19], v[20:21] neg_lo:[0,0,1] neg_hi:[0,0,1]
	v_pk_mul_f32 v[28:29], v[28:29], s[16:17] op_sel_hi:[1,0]
	v_pk_mul_f32 v[18:19], v[18:19], s[16:17] op_sel_hi:[1,0]
	v_pk_mul_f32 v[22:23], v[22:23], s[16:17] op_sel_hi:[1,0]
	v_cvt_pk_bf16_f32 v125, v18, v19
	v_lshlrev_b32_e32 v18, 16, v14
	v_and_b32_e32 v19, 0xffff0000, v14
	v_pk_mul_f32 v[18:19], v[18:19], s[16:17] op_sel_hi:[1,0]
	v_lshlrev_b32_e32 v14, 16, v15
	v_cvt_pk_bf16_f32 v126, v18, v19
	v_add_co_u32_e32 v18, vcc, s28, v194
	v_and_b32_e32 v15, 0xffff0000, v15
	s_nop 0
	v_addc_co_u32_e32 v19, vcc, 0, v195, vcc
	v_add_co_u32_e32 v20, vcc, s28, v190
	v_pk_mul_f32 v[14:15], v[14:15], s[16:17] op_sel_hi:[1,0]
	s_nop 0
	v_addc_co_u32_e32 v21, vcc, 0, v191, vcc
	global_load_dwordx4 v[138:141], v[18:19], off
	global_load_dwordx4 v[142:145], v[20:21], off
	v_cvt_pk_bf16_f32 v127, v14, v15
	v_lshlrev_b32_e32 v14, 16, v16
	v_and_b32_e32 v15, 0xffff0000, v16
	v_pk_mul_f32 v[14:15], v[14:15], s[16:17] op_sel_hi:[1,0]
	v_cvt_pk_bf16_f32 v118, v50, v51
	v_cvt_pk_bf16_f32 v128, v14, v15
	v_lshlrev_b32_e32 v14, 16, v17
	v_and_b32_e32 v15, 0xffff0000, v17
	v_pk_mul_f32 v[14:15], v[14:15], s[16:17] op_sel_hi:[1,0]
	v_cvt_pk_bf16_f32 v120, v28, v29
	v_cvt_pk_bf16_f32 v129, v14, v15
	s_waitcnt vmcnt(8)
	v_lshlrev_b32_e32 v14, 16, v10
	v_and_b32_e32 v15, 0xffff0000, v10
	v_lshlrev_b32_e32 v10, 16, v11
	v_and_b32_e32 v11, 0xffff0000, v11
	v_pk_mul_f32 v[10:11], v[10:11], s[16:17] op_sel_hi:[1,0]
	v_pk_mul_f32 v[14:15], v[14:15], s[16:17] op_sel_hi:[1,0]
	v_cvt_pk_bf16_f32 v147, v10, v11
	v_lshlrev_b32_e32 v10, 16, v12
	v_and_b32_e32 v11, 0xffff0000, v12
	v_pk_mul_f32 v[10:11], v[10:11], s[16:17] op_sel_hi:[1,0]
	v_cvt_pk_bf16_f32 v146, v14, v15
	v_cvt_pk_bf16_f32 v148, v10, v11
	v_lshlrev_b32_e32 v10, 16, v13
	v_and_b32_e32 v11, 0xffff0000, v13
	v_pk_mul_f32 v[10:11], v[10:11], s[16:17] op_sel_hi:[1,0]
	v_mov_b32_e32 v14, v1
	v_cvt_pk_bf16_f32 v149, v10, v11
	v_lshlrev_b32_e32 v10, 16, v6
	v_and_b32_e32 v11, 0xffff0000, v6
	v_lshlrev_b32_e32 v6, 16, v7
	v_and_b32_e32 v7, 0xffff0000, v7
	v_pk_mul_f32 v[6:7], v[6:7], s[16:17] op_sel_hi:[1,0]
	v_pk_mul_f32 v[10:11], v[10:11], s[16:17] op_sel_hi:[1,0]
	v_cvt_pk_bf16_f32 v151, v6, v7
	v_lshlrev_b32_e32 v6, 16, v8
	v_and_b32_e32 v7, 0xffff0000, v8
	v_pk_mul_f32 v[6:7], v[6:7], s[16:17] op_sel_hi:[1,0]
	v_mov_b32_e32 v15, v1
	v_cvt_pk_bf16_f32 v152, v6, v7
	v_lshlrev_b32_e32 v6, 16, v9
	v_and_b32_e32 v7, 0xffff0000, v9
	v_pk_mul_f32 v[6:7], v[6:7], s[16:17] op_sel_hi:[1,0]
	v_cvt_pk_bf16_f32 v121, v22, v23
	v_cvt_pk_bf16_f32 v153, v6, v7
	s_waitcnt vmcnt(4)
	v_lshlrev_b32_e32 v6, 16, v2
	v_and_b32_e32 v7, 0xffff0000, v2
	v_lshlrev_b32_e32 v2, 16, v3
	v_and_b32_e32 v3, 0xffff0000, v3
	v_pk_mul_f32 v[2:3], v[2:3], s[16:17] op_sel_hi:[1,0]
	v_pk_mul_f32 v[6:7], v[6:7], s[16:17] op_sel_hi:[1,0]
	v_cvt_pk_bf16_f32 v155, v2, v3
	v_lshlrev_b32_e32 v2, 16, v4
	v_and_b32_e32 v3, 0xffff0000, v4
	v_pk_mul_f32 v[2:3], v[2:3], s[16:17] op_sel_hi:[1,0]
	v_cvt_pk_bf16_f32 v150, v10, v11
	v_cvt_pk_bf16_f32 v156, v2, v3
	v_lshlrev_b32_e32 v2, 16, v5
	v_and_b32_e32 v3, 0xffff0000, v5
	v_pk_mul_f32 v[2:3], v[2:3], s[16:17] op_sel_hi:[1,0]
	v_cvt_pk_bf16_f32 v154, v6, v7
	v_cvt_pk_bf16_f32 v157, v2, v3
	v_mov_b32_e32 v0, v1
	v_mov_b32_e32 v2, v1
	v_mov_b32_e32 v3, v1
	v_mov_b32_e32 v4, v1
	v_mov_b32_e32 v5, v1
	v_mov_b32_e32 v6, v1
	v_mov_b32_e32 v7, v1
	v_mov_b32_e32 v8, v1
	v_mov_b32_e32 v9, v1
	v_mov_b32_e32 v10, v1
	v_mov_b32_e32 v11, v1
	v_mov_b32_e32 v12, v1
	v_mov_b32_e32 v13, v1
	v_mov_b64_e32 v[46:47], v[14:15]
	v_mov_b64_e32 v[30:31], v[14:15]
	v_mov_b64_e32 v[64:65], v[14:15]
	v_mov_b64_e32 v[44:45], v[12:13]
	v_mov_b64_e32 v[42:43], v[10:11]
	v_mov_b64_e32 v[40:41], v[8:9]
	v_mov_b64_e32 v[38:39], v[6:7]
	v_mov_b64_e32 v[36:37], v[4:5]
	v_mov_b64_e32 v[34:35], v[2:3]
	v_mov_b64_e32 v[32:33], v[0:1]
	v_mov_b64_e32 v[28:29], v[12:13]
	v_mov_b64_e32 v[26:27], v[10:11]
	v_mov_b64_e32 v[24:25], v[8:9]
	v_mov_b64_e32 v[22:23], v[6:7]
	v_mov_b64_e32 v[20:21], v[4:5]
	v_mov_b64_e32 v[18:19], v[2:3]
	v_mov_b64_e32 v[16:17], v[0:1]
	v_mov_b64_e32 v[62:63], v[12:13]
	v_mov_b64_e32 v[60:61], v[10:11]
	v_mov_b64_e32 v[58:59], v[8:9]
	v_mov_b64_e32 v[56:57], v[6:7]
	v_mov_b64_e32 v[54:55], v[4:5]
	v_mov_b64_e32 v[52:53], v[2:3]
	v_mov_b64_e32 v[50:51], v[0:1]
	v_mov_b32_e32 v2, 0
	s_branch .LBB0_849
.LBB0_848:
	s_add_i32 s23, s23, 3
	s_addk_i32 s21, 0xc0
	s_cmp_lt_i32 s23, s19
	s_cbranch_scc0 .LBB0_869

; #define LAS __attribute__((address_space(3)))
; #define MFMA32(a, b, c) __builtin_amdgcn_mfma_f32_32x32x16_bf16((a), (b), (c), 0, 0, 0)
; DI int crow(int r, int hi) { return (r & 3) + 8 * (r >> 2) + 4 * hi; }
; DI float max3f(float a, float b, float c) { float r; asm("v_max3_f32 %0, %1, %2, %3" : "=v"(r) : "v"(a), "v"(b), "v"(c)); return r; }
; DI float max2f(float a, float b) { float r; asm("v_max_f32_e32 %0, %1, %2" : "=v"(r) : "v"(a), "v"(b)); return r; }
; DI void attn_tile(bool MASK, const LAS unsigned char* Ks, const LAS unsigned char* Vs, const bf16x8 (&qr)[6], f32x16& negm, float& mrun, float& lrun, f32x16& o0, f32x16& o1,
;                                        int kv0, int qrow, int r32, int hi) {
;     ...
;         p0 = MFMA32(a0, qr[0], negm); p1 = MFMA32(a1, qr[0], negm);
;     }
; #pragma unroll
;     for (int d0 = 1; d0 < 6; ++d0) {
;         const bf16x8 a0 = *(const LAS bf16x8*)(Ks + r32 * 208 + (2 * d0 + hi) * 16);
;         const bf16x8 a1 = *(const LAS bf16x8*)(Ks + (32 + r32) * 208 + (2 * d0 + hi) * 16);
;         p0 = MFMA32(a0, qr[d0], p0); p1 = MFMA32(a1, qr[d0], p1);
;     }
;     __builtin_amdgcn_s_setprio(0);
;     if (MASK) {
;         asm volatile("" ::: "memory");
; #pragma unroll
;         for (int r = 0; r < 16; ++r) { const int kv = kv0 + crow(r, hi); if (kv > qrow) p0[r] = -INFINITY; if (kv + 32 > qrow) p1[r] = -INFINITY; }
;     }
;     float mxa = max3f(p0[0], p0[1], p1[0]), mxb = max3f(p0[2], p0[3], p1[1]); mxa = max3f(mxa, p1[2], p1[3]);
; #pragma unroll
;     for (int r = 4; r < 16; r += 4) { mxa = max3f(mxa, p0[r], p0[r + 1]); mxb = max3f(mxb, p0[r + 2], p0[r + 3]); mxa = max3f(mxa, p1[r], p1[r + 1]); mxb = max3f(mxb, p1[r + 2], p1[r + 3]); }
;     float mx = max2f(mxa, mxb);
;     mx = max2f(mx, __shfl_xor(mx, 32));
;     if (__any(mx > AT_THR)) {
;         const float dm = max2f(mx, 0.f);
;         const float alpha = __builtin_amdgcn_exp2f(-dm);
;         mrun += dm; lrun *= alpha;
; #pragma unroll
;         for (int r = 0; r < 16; ++r) { o0[r] *= alpha; o1[r] *= alpha; p0[r] -= dm; p1[r] -= dm; negm[r] = -mrun; }
;     }
.Lat_m0:
	v_add_u32_e32 v3, v205, v208
	v_add_u32_e32 v0, 0x4000, v3
	v_add_u32_e32 v3, 0x3000, v3
	s_waitcnt lgkmcnt(5)
	v_mfma_f32_32x32x16_bf16 v[66:81], v[226:229], v[154:157], v[50:65]
	ds_read2_b64 v[226:229], v3 offset0:128 offset1:130
	s_waitcnt lgkmcnt(5)
	v_mfma_f32_32x32x16_bf16 v[66:81], v[230:233], v[150:153], v[66:81]
	ds_read2_b64 v[230:233], v0 offset0:160 offset1:162
	s_nop 3
	v_sub_u32_e32 v251, v49, v207
	v_subrev_u32_e32 v251, s21, v251
	v_cmp_le_i32_e64 s[98:99], 0, v251
	v_cmp_le_i32_e64 s[100:101], 1, v251
	v_cmp_le_i32_e64 vcc, 2, v251
	v_cndmask_b32_e64 v82, v212, v82, s[98:99]
	v_cmp_le_i32_e64 s[98:99], 3, v251
	v_cndmask_b32_e64 v83, v212, v83, s[100:101]
	v_cmp_le_i32_e64 s[100:101], 8, v251
	v_cndmask_b32_e64 v84, v212, v84, vcc
	s_waitcnt lgkmcnt(5)
	v_mfma_f32_32x32x16_bf16 v[66:81], v[234:237], v[146:149], v[66:81]
	ds_read2_b64 v[234:237], v3 offset0:132 offset1:134
	v_cmp_le_i32_e64 vcc, 9, v251
	v_cndmask_b32_e64 v85, v212, v85, s[98:99]
	v_cmp_le_i32_e64 s[98:99], 10, v251
	v_cndmask_b32_e64 v86, v212, v86, s[100:101]
	v_cmp_le_i32_e64 s[100:101], 11, v251
	v_cndmask_b32_e64 v87, v212, v87, vcc
	v_cmp_le_i32_e64 vcc, 16, v251
	v_cndmask_b32_e64 v88, v212, v88, s[98:99]
	s_waitcnt lgkmcnt(5)
	v_mfma_f32_32x32x16_bf16 v[66:81], v[238:241], v[126:129], v[66:81]
	ds_read2_b64 v[238:241], v0 offset0:164 offset1:166
	v_cmp_le_i32_e64 s[98:99], 17, v251
	v_cndmask_b32_e64 v89, v212, v89, s[100:101]
	v_cmp_le_i32_e64 s[100:101], 18, v251
	v_cndmask_b32_e64 v90, v212, v90, vcc
	v_cmp_le_i32_e64 vcc, 19, v251
	v_cndmask_b32_e64 v91, v212, v91, s[98:99]
	v_cmp_le_i32_e64 s[98:99], 24, v251
	v_cndmask_b32_e64 v92, v212, v92, s[100:101]
	s_waitcnt lgkmcnt(5)
	v_mfma_f32_32x32x16_bf16 v[66:81], v[242:245], v[122:125], v[66:81]
	ds_read2_b64 v[242:245], v3 offset0:136 offset1:138
	v_cmp_le_i32_e64 s[100:101], 25, v251
	v_cndmask_b32_e64 v93, v212, v93, vcc
	v_cmp_le_i32_e64 vcc, 26, v251
	v_cndmask_b32_e64 v94, v212, v94, s[98:99]
	v_cmp_le_i32_e64 s[98:99], 27, v251
	v_cndmask_b32_e64 v95, v212, v95, s[100:101]
	v_cndmask_b32_e64 v96, v212, v96, vcc
	v_cndmask_b32_e64 v97, v212, v97, s[98:99]
	s_waitcnt lgkmcnt(5)
	v_mfma_f32_32x32x16_bf16 v[66:81], v[246:249], v[118:121], v[66:81]
	ds_read2_b64 v[246:249], v0 offset0:168 offset1:170
	s_setprio 0
	v_exp_f32_e32 v214, v82
	v_exp_f32_e32 v215, v83
	v_max3_f32 v159, v82, v83, v84
	v_exp_f32_e32 v216, v84
	v_exp_f32_e32 v217, v85
	v_max3_f32 v250, v85, v86, v87
	v_exp_f32_e32 v218, v86
	v_exp_f32_e32 v219, v87
	v_max3_f32 v159, v159, v88, v89
	v_exp_f32_e32 v220, v88
	v_exp_f32_e32 v221, v89
	v_max3_f32 v250, v250, v90, v91
	v_exp_f32_e32 v222, v90
	v_exp_f32_e32 v223, v91
	v_max3_f32 v159, v159, v92, v93
	v_exp_f32_e32 v224, v92
	v_exp_f32_e32 v225, v93
	v_max3_f32 v250, v250, v94, v95
	v_exp_f32_e32 v12, v94
	v_exp_f32_e32 v13, v95
	v_max3_f32 v159, v159, v96, v97
	v_exp_f32_e32 v14, v96
	v_exp_f32_e32 v15, v97
	v_cmp_le_i32_e64 s[98:99], 32, v251
	v_cmp_le_i32_e64 s[100:101], 33, v251
	v_cmp_le_i32_e64 vcc, 34, v251
	v_cndmask_b32_e64 v66, v212, v66, s[98:99]
	v_cmp_le_i32_e64 s[98:99], 35, v251
	v_cndmask_b32_e64 v67, v212, v67, s[100:101]
	v_cmp_le_i32_e64 s[100:101], 40, v251
	v_cndmask_b32_e64 v68, v212, v68, vcc
	v_cmp_le_i32_e64 vcc, 41, v251
	v_cndmask_b32_e64 v69, v212, v69, s[98:99]
	v_cmp_le_i32_e64 s[98:99], 42, v251
	v_cndmask_b32_e64 v70, v212, v70, s[100:101]
	v_cmp_le_i32_e64 s[100:101], 43, v251
	v_cndmask_b32_e64 v71, v212, v71, vcc
	v_cmp_le_i32_e64 vcc, 48, v251
	v_cndmask_b32_e64 v72, v212, v72, s[98:99]
	v_cmp_le_i32_e64 s[98:99], 49, v251
	v_cndmask_b32_e64 v73, v212, v73, s[100:101]
	v_cmp_le_i32_e64 s[100:101], 50, v251
	v_cndmask_b32_e64 v74, v212, v74, vcc
	v_cmp_le_i32_e64 vcc, 51, v251
	v_cndmask_b32_e64 v75, v212, v75, s[98:99]
	v_cmp_le_i32_e64 s[98:99], 56, v251
	v_cndmask_b32_e64 v76, v212, v76, s[100:101]
	v_cmp_le_i32_e64 s[100:101], 57, v251
	v_cndmask_b32_e64 v77, v212, v77, vcc
	v_cmp_le_i32_e64 vcc, 58, v251
	v_cndmask_b32_e64 v78, v212, v78, s[98:99]
	v_cmp_le_i32_e64 s[98:99], 59, v251
	v_cndmask_b32_e64 v79, v212, v79, s[100:101]
	v_cndmask_b32_e64 v80, v212, v80, vcc
	v_cndmask_b32_e64 v81, v212, v81, s[98:99]
	s_nop 1
	v_max3_f32 v159, v159, v66, v67
	v_max3_f32 v250, v250, v68, v69
	v_max3_f32 v159, v159, v70, v71
	v_max3_f32 v250, v250, v72, v73
	v_max3_f32 v159, v159, v74, v75
	v_max3_f32 v250, v250, v76, v77
	v_max3_f32 v159, v159, v78, v79
	v_max3_f32 v250, v250, v80, v81
	v_max_f32_e32 v0, v159, v250
	v_mov_b32_e32 v3, v0
	s_nop 1
	v_permlane32_swap_b32_e32 v0, v3
	v_max_f32_e32 v0, v0, v3
	s_nop 0
	v_cmp_lt_f32_e32 vcc, s30, v0
	s_cbranch_vccnz .Lat_r0
	s_branch .Lat_c0

; #define LAS __attribute__((address_space(3)))
; #define MFMA32(a, b, c) __builtin_amdgcn_mfma_f32_32x32x16_bf16((a), (b), (c), 0, 0, 0)
; DI int crow(int r, int hi) { return (r & 3) + 8 * (r >> 2) + 4 * hi; }
; DI float max3f(float a, float b, float c) { float r; asm("v_max3_f32 %0, %1, %2, %3" : "=v"(r) : "v"(a), "v"(b), "v"(c)); return r; }
; DI float max2f(float a, float b) { float r; asm("v_max_f32_e32 %0, %1, %2" : "=v"(r) : "v"(a), "v"(b)); return r; }
; DI void attn_tile(bool MASK, const LAS unsigned char* Ks, const LAS unsigned char* Vs, const bf16x8 (&qr)[6], f32x16& negm, float& mrun, float& lrun, f32x16& o0, f32x16& o1,
;                                        int kv0, int qrow, int r32, int hi) {
;     ...
;         p0 = MFMA32(a0, qr[0], negm); p1 = MFMA32(a1, qr[0], negm);
;     }
; #pragma unroll
;     for (int d0 = 1; d0 < 6; ++d0) {
;         const bf16x8 a0 = *(const LAS bf16x8*)(Ks + r32 * 208 + (2 * d0 + hi) * 16);
;         const bf16x8 a1 = *(const LAS bf16x8*)(Ks + (32 + r32) * 208 + (2 * d0 + hi) * 16);
;         p0 = MFMA32(a0, qr[d0], p0); p1 = MFMA32(a1, qr[d0], p1);
;     }
;     __builtin_amdgcn_s_setprio(0);
;     if (MASK) {
;         asm volatile("" ::: "memory");
; #pragma unroll
;         for (int r = 0; r < 16; ++r) { const int kv = kv0 + crow(r, hi); if (kv > qrow) p0[r] = -INFINITY; if (kv + 32 > qrow) p1[r] = -INFINITY; }
;     }
;     float mxa = max3f(p0[0], p0[1], p1[0]), mxb = max3f(p0[2], p0[3], p1[1]); mxa = max3f(mxa, p1[2], p1[3]);
; #pragma unroll
;     for (int r = 4; r < 16; r += 4) { mxa = max3f(mxa, p0[r], p0[r + 1]); mxb = max3f(mxb, p0[r + 2], p0[r + 3]); mxa = max3f(mxa, p1[r], p1[r + 1]); mxb = max3f(mxb, p1[r + 2], p1[r + 3]); }
;     float mx = max2f(mxa, mxb);
;     mx = max2f(mx, __shfl_xor(mx, 32));
;     if (__any(mx > AT_THR)) {
;         const float dm = max2f(mx, 0.f);
;         const float alpha = __builtin_amdgcn_exp2f(-dm);
;         mrun += dm; lrun *= alpha;
; #pragma unroll
;         for (int r = 0; r < 16; ++r) { o0[r] *= alpha; o1[r] *= alpha; p0[r] -= dm; p1[r] -= dm; negm[r] = -mrun; }
;     }
.Lat_m1:
	v_add_u32_e32 v3, v205, v208
	v_add_u32_e32 v0, 0x9800, v3
	v_add_u32_e32 v3, 0x8800, v3
	s_waitcnt lgkmcnt(5)
	v_mfma_f32_32x32x16_bf16 v[66:81], v[226:229], v[154:157], v[50:65]
	ds_read2_b64 v[226:229], v3 offset0:64 offset1:66
	s_waitcnt lgkmcnt(5)
	v_mfma_f32_32x32x16_bf16 v[66:81], v[230:233], v[150:153], v[66:81]
	ds_read2_b64 v[230:233], v0 offset0:96 offset1:98
	s_nop 3
	v_sub_u32_e32 v251, v49, v207
	v_subrev_u32_e32 v251, s21, v251
	v_subrev_u32_e32 v251, 64, v251
	v_cmp_le_i32_e64 s[98:99], 0, v251
	v_cmp_le_i32_e64 s[100:101], 1, v251
	v_cmp_le_i32_e64 vcc, 2, v251
	v_cndmask_b32_e64 v82, v212, v82, s[98:99]
	v_cmp_le_i32_e64 s[98:99], 3, v251
	v_cndmask_b32_e64 v83, v212, v83, s[100:101]
	v_cmp_le_i32_e64 s[100:101], 8, v251
	v_cndmask_b32_e64 v84, v212, v84, vcc
	s_waitcnt lgkmcnt(5)
	v_mfma_f32_32x32x16_bf16 v[66:81], v[234:237], v[146:149], v[66:81]
	ds_read2_b64 v[234:237], v3 offset0:68 offset1:70
	v_cmp_le_i32_e64 vcc, 9, v251
	v_cndmask_b32_e64 v85, v212, v85, s[98:99]
	v_cmp_le_i32_e64 s[98:99], 10, v251
	v_cndmask_b32_e64 v86, v212, v86, s[100:101]
	v_cmp_le_i32_e64 s[100:101], 11, v251
	v_cndmask_b32_e64 v87, v212, v87, vcc
	v_cmp_le_i32_e64 vcc, 16, v251
	v_cndmask_b32_e64 v88, v212, v88, s[98:99]
	s_waitcnt lgkmcnt(5)
	v_mfma_f32_32x32x16_bf16 v[66:81], v[238:241], v[126:129], v[66:81]
	ds_read2_b64 v[238:241], v0 offset0:100 offset1:102
	v_cmp_le_i32_e64 s[98:99], 17, v251
	v_cndmask_b32_e64 v89, v212, v89, s[100:101]
	v_cmp_le_i32_e64 s[100:101], 18, v251
	v_cndmask_b32_e64 v90, v212, v90, vcc
	v_cmp_le_i32_e64 vcc, 19, v251
	v_cndmask_b32_e64 v91, v212, v91, s[98:99]
	v_cmp_le_i32_e64 s[98:99], 24, v251
	v_cndmask_b32_e64 v92, v212, v92, s[100:101]
	s_waitcnt lgkmcnt(5)
	v_mfma_f32_32x32x16_bf16 v[66:81], v[242:245], v[122:125], v[66:81]
	ds_read2_b64 v[242:245], v3 offset0:72 offset1:74
	v_cmp_le_i32_e64 s[100:101], 25, v251
	v_cndmask_b32_e64 v93, v212, v93, vcc
	v_cmp_le_i32_e64 vcc, 26, v251
	v_cndmask_b32_e64 v94, v212, v94, s[98:99]
	v_cmp_le_i32_e64 s[98:99], 27, v251
	v_cndmask_b32_e64 v95, v212, v95, s[100:101]
	v_cndmask_b32_e64 v96, v212, v96, vcc
	v_cndmask_b32_e64 v97, v212, v97, s[98:99]
	s_waitcnt lgkmcnt(5)
	v_mfma_f32_32x32x16_bf16 v[66:81], v[246:249], v[118:121], v[66:81]
	ds_read2_b64 v[246:249], v0 offset0:104 offset1:106
	s_setprio 0
	v_exp_f32_e32 v214, v82
	v_exp_f32_e32 v215, v83
	v_max3_f32 v159, v82, v83, v84
	v_exp_f32_e32 v216, v84
	v_exp_f32_e32 v217, v85
	v_max3_f32 v250, v85, v86, v87
	v_exp_f32_e32 v218, v86
	v_exp_f32_e32 v219, v87
	v_max3_f32 v159, v159, v88, v89
	v_exp_f32_e32 v220, v88
	v_exp_f32_e32 v221, v89
	v_max3_f32 v250, v250, v90, v91
	v_exp_f32_e32 v222, v90
	v_exp_f32_e32 v223, v91
	v_max3_f32 v159, v159, v92, v93
	v_exp_f32_e32 v224, v92
	v_exp_f32_e32 v225, v93
	v_max3_f32 v250, v250, v94, v95
	v_exp_f32_e32 v12, v94
	v_exp_f32_e32 v13, v95
	v_max3_f32 v159, v159, v96, v97
	v_exp_f32_e32 v14, v96
	v_exp_f32_e32 v15, v97
	v_cmp_le_i32_e64 s[98:99], 32, v251
	v_cmp_le_i32_e64 s[100:101], 33, v251
	v_cmp_le_i32_e64 vcc, 34, v251
	v_cndmask_b32_e64 v66, v212, v66, s[98:99]
	v_cmp_le_i32_e64 s[98:99], 35, v251
	v_cndmask_b32_e64 v67, v212, v67, s[100:101]
	v_cmp_le_i32_e64 s[100:101], 40, v251
	v_cndmask_b32_e64 v68, v212, v68, vcc
	v_cmp_le_i32_e64 vcc, 41, v251
	v_cndmask_b32_e64 v69, v212, v69, s[98:99]
	v_cmp_le_i32_e64 s[98:99], 42, v251
	v_cndmask_b32_e64 v70, v212, v70, s[100:101]
	v_cmp_le_i32_e64 s[100:101], 43, v251
	v_cndmask_b32_e64 v71, v212, v71, vcc
	v_cmp_le_i32_e64 vcc, 48, v251
	v_cndmask_b32_e64 v72, v212, v72, s[98:99]
	v_cmp_le_i32_e64 s[98:99], 49, v251
	v_cndmask_b32_e64 v73, v212, v73, s[100:101]
	v_cmp_le_i32_e64 s[100:101], 50, v251
	v_cndmask_b32_e64 v74, v212, v74, vcc
	v_cmp_le_i32_e64 vcc, 51, v251
	v_cndmask_b32_e64 v75, v212, v75, s[98:99]
	v_cmp_le_i32_e64 s[98:99], 56, v251
	v_cndmask_b32_e64 v76, v212, v76, s[100:101]
	v_cmp_le_i32_e64 s[100:101], 57, v251
	v_cndmask_b32_e64 v77, v212, v77, vcc
	v_cmp_le_i32_e64 vcc, 58, v251
	v_cndmask_b32_e64 v78, v212, v78, s[98:99]
	v_cmp_le_i32_e64 s[98:99], 59, v251
	v_cndmask_b32_e64 v79, v212, v79, s[100:101]
	v_cndmask_b32_e64 v80, v212, v80, vcc
	v_cndmask_b32_e64 v81, v212, v81, s[98:99]
	s_nop 1
	v_max3_f32 v159, v159, v66, v67
	v_max3_f32 v250, v250, v68, v69
	v_max3_f32 v159, v159, v70, v71
	v_max3_f32 v250, v250, v72, v73
	v_max3_f32 v159, v159, v74, v75
	v_max3_f32 v250, v250, v76, v77
	v_max3_f32 v159, v159, v78, v79
	v_max3_f32 v250, v250, v80, v81
	v_max_f32_e32 v0, v159, v250
	v_mov_b32_e32 v3, v0
	s_nop 1
	v_permlane32_swap_b32_e32 v0, v3
	v_max_f32_e32 v0, v0, v3
	s_nop 0
	v_cmp_lt_f32_e32 vcc, s30, v0
	s_cbranch_vccnz .Lat_r1
	s_branch .Lat_c1

; #define LAS __attribute__((address_space(3)))
; #define MFMA32(a, b, c) __builtin_amdgcn_mfma_f32_32x32x16_bf16((a), (b), (c), 0, 0, 0)
; DI int crow(int r, int hi) { return (r & 3) + 8 * (r >> 2) + 4 * hi; }
; DI float max3f(float a, float b, float c) { float r; asm("v_max3_f32 %0, %1, %2, %3" : "=v"(r) : "v"(a), "v"(b), "v"(c)); return r; }
; DI float max2f(float a, float b) { float r; asm("v_max_f32_e32 %0, %1, %2" : "=v"(r) : "v"(a), "v"(b)); return r; }
; DI void attn_tile(bool MASK, const LAS unsigned char* Ks, const LAS unsigned char* Vs, const bf16x8 (&qr)[6], f32x16& negm, float& mrun, float& lrun, f32x16& o0, f32x16& o1,
;                                        int kv0, int qrow, int r32, int hi) {
;     ...
;         p0 = MFMA32(a0, qr[0], negm); p1 = MFMA32(a1, qr[0], negm);
;     }
; #pragma unroll
;     for (int d0 = 1; d0 < 6; ++d0) {
;         const bf16x8 a0 = *(const LAS bf16x8*)(Ks + r32 * 208 + (2 * d0 + hi) * 16);
;         const bf16x8 a1 = *(const LAS bf16x8*)(Ks + (32 + r32) * 208 + (2 * d0 + hi) * 16);
;         p0 = MFMA32(a0, qr[d0], p0); p1 = MFMA32(a1, qr[d0], p1);
;     }
;     __builtin_amdgcn_s_setprio(0);
;     if (MASK) {
;         asm volatile("" ::: "memory");
; #pragma unroll
;         for (int r = 0; r < 16; ++r) { const int kv = kv0 + crow(r, hi); if (kv > qrow) p0[r] = -INFINITY; if (kv + 32 > qrow) p1[r] = -INFINITY; }
;     }
;     float mxa = max3f(p0[0], p0[1], p1[0]), mxb = max3f(p0[2], p0[3], p1[1]); mxa = max3f(mxa, p1[2], p1[3]);
; #pragma unroll
;     for (int r = 4; r < 16; r += 4) { mxa = max3f(mxa, p0[r], p0[r + 1]); mxb = max3f(mxb, p0[r + 2], p0[r + 3]); mxa = max3f(mxa, p1[r], p1[r + 1]); mxb = max3f(mxb, p1[r + 2], p1[r + 3]); }
;     float mx = max2f(mxa, mxb);
;     mx = max2f(mx, __shfl_xor(mx, 32));
;     if (__any(mx > AT_THR)) {
;         const float dm = max2f(mx, 0.f);
;         const float alpha = __builtin_amdgcn_exp2f(-dm);
;         mrun += dm; lrun *= alpha;
; #pragma unroll
;         for (int r = 0; r < 16; ++r) { o0[r] *= alpha; o1[r] *= alpha; p0[r] -= dm; p1[r] -= dm; negm[r] = -mrun; }
;     }
.Lat_m2:
	v_add_u32_e32 v3, v205, v208
	v_add_u32_e32 v0, 0xf000, v3
	v_add_u32_e32 v3, 0xe000, v3
	s_waitcnt lgkmcnt(5)
	v_mfma_f32_32x32x16_bf16 v[66:81], v[226:229], v[154:157], v[50:65]
	ds_read2_b64 v[226:229], v3 offset1:2
	s_waitcnt lgkmcnt(5)
	v_mfma_f32_32x32x16_bf16 v[66:81], v[230:233], v[150:153], v[66:81]
	ds_read2_b64 v[230:233], v0 offset0:32 offset1:34
	s_nop 3
	v_sub_u32_e32 v251, v49, v207
	v_subrev_u32_e32 v251, s21, v251
	v_subrev_u32_e32 v251, 0x80, v251
	v_cmp_le_i32_e64 s[98:99], 0, v251
	v_cmp_le_i32_e64 s[100:101], 1, v251
	v_cmp_le_i32_e64 vcc, 2, v251
	v_cndmask_b32_e64 v82, v212, v82, s[98:99]
	v_cmp_le_i32_e64 s[98:99], 3, v251
	v_cndmask_b32_e64 v83, v212, v83, s[100:101]
	v_cmp_le_i32_e64 s[100:101], 8, v251
	v_cndmask_b32_e64 v84, v212, v84, vcc
	s_waitcnt lgkmcnt(5)
	v_mfma_f32_32x32x16_bf16 v[66:81], v[234:237], v[146:149], v[66:81]
	ds_read2_b64 v[234:237], v3 offset0:4 offset1:6
	v_cmp_le_i32_e64 vcc, 9, v251
	v_cndmask_b32_e64 v85, v212, v85, s[98:99]
	v_cmp_le_i32_e64 s[98:99], 10, v251
	v_cndmask_b32_e64 v86, v212, v86, s[100:101]
	v_cmp_le_i32_e64 s[100:101], 11, v251
	v_cndmask_b32_e64 v87, v212, v87, vcc
	v_cmp_le_i32_e64 vcc, 16, v251
	v_cndmask_b32_e64 v88, v212, v88, s[98:99]
	s_waitcnt lgkmcnt(5)
	v_mfma_f32_32x32x16_bf16 v[66:81], v[238:241], v[126:129], v[66:81]
	ds_read2_b64 v[238:241], v0 offset0:36 offset1:38
	v_cmp_le_i32_e64 s[98:99], 17, v251
	v_cndmask_b32_e64 v89, v212, v89, s[100:101]
	v_cmp_le_i32_e64 s[100:101], 18, v251
	v_cndmask_b32_e64 v90, v212, v90, vcc
	v_cmp_le_i32_e64 vcc, 19, v251
	v_cndmask_b32_e64 v91, v212, v91, s[98:99]
	v_cmp_le_i32_e64 s[98:99], 24, v251
	v_cndmask_b32_e64 v92, v212, v92, s[100:101]
	s_waitcnt lgkmcnt(5)
	v_mfma_f32_32x32x16_bf16 v[66:81], v[242:245], v[122:125], v[66:81]
	ds_read2_b64 v[242:245], v3 offset0:8 offset1:10
	v_cmp_le_i32_e64 s[100:101], 25, v251
	v_cndmask_b32_e64 v93, v212, v93, vcc
	v_cmp_le_i32_e64 vcc, 26, v251
	v_cndmask_b32_e64 v94, v212, v94, s[98:99]
	v_cmp_le_i32_e64 s[98:99], 27, v251
	v_cndmask_b32_e64 v95, v212, v95, s[100:101]
	v_cndmask_b32_e64 v96, v212, v96, vcc
	v_cndmask_b32_e64 v97, v212, v97, s[98:99]
	s_waitcnt lgkmcnt(5)
	v_mfma_f32_32x32x16_bf16 v[66:81], v[246:249], v[118:121], v[66:81]
	ds_read2_b64 v[246:249], v0 offset0:40 offset1:42
	s_setprio 0
	v_exp_f32_e32 v214, v82
	v_exp_f32_e32 v215, v83
	v_max3_f32 v159, v82, v83, v84
	v_exp_f32_e32 v216, v84
	v_exp_f32_e32 v217, v85
	v_max3_f32 v250, v85, v86, v87
	v_exp_f32_e32 v218, v86
	v_exp_f32_e32 v219, v87
	v_max3_f32 v159, v159, v88, v89
	v_exp_f32_e32 v220, v88
	v_exp_f32_e32 v221, v89
	v_max3_f32 v250, v250, v90, v91
	v_exp_f32_e32 v222, v90
	v_exp_f32_e32 v223, v91
	v_max3_f32 v159, v159, v92, v93
	v_exp_f32_e32 v224, v92
	v_exp_f32_e32 v225, v93
	v_max3_f32 v250, v250, v94, v95
	v_exp_f32_e32 v12, v94
	v_exp_f32_e32 v13, v95
	v_max3_f32 v159, v159, v96, v97
	v_exp_f32_e32 v14, v96
	v_exp_f32_e32 v15, v97
	v_cmp_le_i32_e64 s[98:99], 32, v251
	v_cmp_le_i32_e64 s[100:101], 33, v251
	v_cmp_le_i32_e64 vcc, 34, v251
	v_cndmask_b32_e64 v66, v212, v66, s[98:99]
	v_cmp_le_i32_e64 s[98:99], 35, v251
	v_cndmask_b32_e64 v67, v212, v67, s[100:101]
	v_cmp_le_i32_e64 s[100:101], 40, v251
	v_cndmask_b32_e64 v68, v212, v68, vcc
	v_cmp_le_i32_e64 vcc, 41, v251
	v_cndmask_b32_e64 v69, v212, v69, s[98:99]
	v_cmp_le_i32_e64 s[98:99], 42, v251
	v_cndmask_b32_e64 v70, v212, v70, s[100:101]
	v_cmp_le_i32_e64 s[100:101], 43, v251
	v_cndmask_b32_e64 v71, v212, v71, vcc
	v_cmp_le_i32_e64 vcc, 48, v251
	v_cndmask_b32_e64 v72, v212, v72, s[98:99]
	v_cmp_le_i32_e64 s[98:99], 49, v251
	v_cndmask_b32_e64 v73, v212, v73, s[100:101]
	v_cmp_le_i32_e64 s[100:101], 50, v251
	v_cndmask_b32_e64 v74, v212, v74, vcc
	v_cmp_le_i32_e64 vcc, 51, v251
	v_cndmask_b32_e64 v75, v212, v75, s[98:99]
	v_cmp_le_i32_e64 s[98:99], 56, v251
	v_cndmask_b32_e64 v76, v212, v76, s[100:101]
	v_cmp_le_i32_e64 s[100:101], 57, v251
	v_cndmask_b32_e64 v77, v212, v77, vcc
	v_cmp_le_i32_e64 vcc, 58, v251
	v_cndmask_b32_e64 v78, v212, v78, s[98:99]
	v_cmp_le_i32_e64 s[98:99], 59, v251
	v_cndmask_b32_e64 v79, v212, v79, s[100:101]
	v_cndmask_b32_e64 v80, v212, v80, vcc
	v_cndmask_b32_e64 v81, v212, v81, s[98:99]
	s_nop 1
	v_max3_f32 v159, v159, v66, v67
	v_max3_f32 v250, v250, v68, v69
	v_max3_f32 v159, v159, v70, v71
	v_max3_f32 v250, v250, v72, v73
	v_max3_f32 v159, v159, v74, v75
	v_max3_f32 v250, v250, v76, v77
	v_max3_f32 v159, v159, v78, v79
	v_max3_f32 v250, v250, v80, v81
	v_max_f32_e32 v0, v159, v250
	v_mov_b32_e32 v3, v0
	s_nop 1
	v_permlane32_swap_b32_e32 v0, v3
	v_max_f32_e32 v0, v0, v3
	s_nop 0
	v_cmp_lt_f32_e32 vcc, s30, v0
	s_cbranch_vccnz .Lat_r2
	s_branch .Lat_c2
